# asm guide 7.3: stick-breaking unit epilogue stores widened, v_permlane32_swap pairs + 8 dwordx4 instead of 16 dwordx2
# speedup vs baseline: 1.0105x; 1.0105x over previous
.LBB0_471:
	v_lshlrev_b64 v[64:65], 12, v[150:151]
	s_waitcnt lgkmcnt(0)
	v_lshl_add_u64 v[64:65], s[64:65], 0, v[64:65]
	v_lshl_add_u64 v[64:65], s[56:57], 1, v[64:65]
	v_lshl_add_u64 v[64:65], v[192:193], 2, v[64:65]
	s_mov_b64 s[10:11], 0x1fa00000
	v_lshl_add_u64 v[66:67], v[64:65], 0, s[10:11]
	v_cvt_pk_bf16_f32 v48, v48, v49
	v_cvt_pk_bf16_f32 v49, v50, v51
	v_cvt_pk_bf16_f32 v50, v52, v53
	v_cvt_pk_bf16_f32 v51, v54, v55
	v_cvt_pk_bf16_f32 v56, v56, v57
	v_cvt_pk_bf16_f32 v57, v58, v59
	v_cvt_pk_bf16_f32 v58, v60, v61
	v_cvt_pk_bf16_f32 v59, v62, v63
	v_permlane32_swap_b32_e32 v48, v50
	v_permlane32_swap_b32_e32 v49, v51
	v_permlane32_swap_b32_e32 v56, v58
	v_permlane32_swap_b32_e32 v57, v59
	global_store_dwordx4 v[66:67], v[48:51], off
	global_store_dwordx4 v[66:67], v[56:59], off offset:32
	v_cvt_pk_bf16_f32 v32, v32, v33
	v_cvt_pk_bf16_f32 v33, v34, v35
	v_cvt_pk_bf16_f32 v34, v36, v37
	v_cvt_pk_bf16_f32 v35, v38, v39
	v_cvt_pk_bf16_f32 v40, v40, v41
	v_cvt_pk_bf16_f32 v41, v42, v43
	v_cvt_pk_bf16_f32 v42, v44, v45
	v_cvt_pk_bf16_f32 v43, v46, v47
	v_permlane32_swap_b32_e32 v32, v34
	v_permlane32_swap_b32_e32 v33, v35
	v_permlane32_swap_b32_e32 v40, v42
	v_permlane32_swap_b32_e32 v41, v43
	global_store_dwordx4 v[66:67], v[32:35], off offset:64
	global_store_dwordx4 v[66:67], v[40:43], off offset:96
	v_cvt_pk_bf16_f32 v16, v16, v17
	v_cvt_pk_bf16_f32 v17, v18, v19
	v_cvt_pk_bf16_f32 v18, v20, v21
	v_cvt_pk_bf16_f32 v19, v22, v23
	v_cvt_pk_bf16_f32 v24, v24, v25
	v_cvt_pk_bf16_f32 v25, v26, v27
	v_cvt_pk_bf16_f32 v26, v28, v29
	v_cvt_pk_bf16_f32 v27, v30, v31
	v_permlane32_swap_b32_e32 v16, v18
	v_permlane32_swap_b32_e32 v17, v19
	v_permlane32_swap_b32_e32 v24, v26
	v_permlane32_swap_b32_e32 v25, v27
	global_store_dwordx4 v[66:67], v[16:19], off offset:128
	global_store_dwordx4 v[66:67], v[24:27], off offset:160
	v_cvt_pk_bf16_f32 v0, v0, v1
	v_cvt_pk_bf16_f32 v1, v2, v3
	v_cvt_pk_bf16_f32 v2, v4, v5
	v_cvt_pk_bf16_f32 v3, v6, v7
	v_cvt_pk_bf16_f32 v8, v8, v9
	v_cvt_pk_bf16_f32 v9, v10, v11
	v_cvt_pk_bf16_f32 v10, v12, v13
	v_cvt_pk_bf16_f32 v11, v14, v15
	v_permlane32_swap_b32_e32 v0, v2
	v_permlane32_swap_b32_e32 v1, v3
	v_permlane32_swap_b32_e32 v8, v10
	v_permlane32_swap_b32_e32 v9, v11
	global_store_dwordx4 v[66:67], v[0:3], off offset:192
	global_store_dwordx4 v[66:67], v[8:11], off offset:224
	s_barrier
	s_mov_b64 s[10:11], 0
